# side CUs' item loop software-pipelined: previous item's LDS read-back and stores overlap the current item's load latency
# speedup vs baseline: 1.0090x; 1.0031x over previous
; #define LAS __attribute__((address_space(3)))
; #define GAS __attribute__((address_space(1)))
; __device__ __forceinline__ void p0_transpose_item(const float* Wsrc  , int ldw, bf16_t* dst  , int ldt, LAS float* scr, int lane) {
;     const int r = lane >> 4, c4 = lane & 15;
;     f32x4 v[16];
; #pragma unroll
;     for (int i = 0; i < 16; ++i) v[i] = __builtin_nontemporal_load((const GAS f32x4*)(Wsrc + (size_t)(4 * i + r) * ldw + 4 * c4));
.LBB0_315:
	v_mul_u32_u24_e32 v2, s46, v7
	v_lshl_add_u64 v[122:123], s[44:45], 0, v[4:5]
	v_lshlrev_b32_e32 v2, 2, v2
	v_lshl_add_u64 v[62:63], v[122:123], 0, v[2:3]
	v_mul_u32_u24_e32 v2, s46, v10
	v_lshlrev_b32_e32 v2, 2, v2
	v_lshl_add_u64 v[66:67], v[122:123], 0, v[2:3]
	v_mul_u32_u24_e32 v2, s46, v11
	v_lshlrev_b32_e32 v2, 2, v2
	v_lshl_add_u64 v[70:71], v[122:123], 0, v[2:3]
	v_mul_u32_u24_e32 v2, s46, v12
	v_lshlrev_b32_e32 v2, 2, v2
	v_lshl_add_u64 v[74:75], v[122:123], 0, v[2:3]
	v_mul_u32_u24_e32 v2, s46, v13
	v_lshlrev_b32_e32 v2, 2, v2
	v_lshl_add_u64 v[78:79], v[122:123], 0, v[2:3]
	v_mul_u32_u24_e32 v2, s46, v14
	v_lshlrev_b32_e32 v2, 2, v2
	v_lshl_add_u64 v[82:83], v[122:123], 0, v[2:3]
	v_mul_u32_u24_e32 v2, s46, v15
	v_lshlrev_b32_e32 v2, 2, v2
	v_lshl_add_u64 v[86:87], v[122:123], 0, v[2:3]
	v_mul_u32_u24_e32 v2, s46, v16
	v_lshlrev_b32_e32 v2, 2, v2
	v_lshl_add_u64 v[90:91], v[122:123], 0, v[2:3]
	v_mul_u32_u24_e32 v2, s46, v17
	v_lshlrev_b32_e32 v2, 2, v2
	v_lshl_add_u64 v[94:95], v[122:123], 0, v[2:3]
	v_mul_u32_u24_e32 v2, s46, v18
	v_lshlrev_b32_e32 v2, 2, v2
	v_lshl_add_u64 v[98:99], v[122:123], 0, v[2:3]
	v_mul_u32_u24_e32 v2, s46, v19
	v_lshlrev_b32_e32 v2, 2, v2
	v_lshl_add_u64 v[102:103], v[122:123], 0, v[2:3]
	v_mul_u32_u24_e32 v2, s46, v20
	v_lshlrev_b32_e32 v2, 2, v2
	v_lshl_add_u64 v[106:107], v[122:123], 0, v[2:3]
	v_mul_u32_u24_e32 v2, s46, v21
	v_lshlrev_b32_e32 v2, 2, v2
	v_lshl_add_u64 v[110:111], v[122:123], 0, v[2:3]
	v_mul_u32_u24_e32 v2, s46, v22
	v_lshlrev_b32_e32 v2, 2, v2
	v_lshl_add_u64 v[114:115], v[122:123], 0, v[2:3]
	global_load_dwordx4 v[62:65], v[62:63], off nt
	s_nop 0
	global_load_dwordx4 v[66:69], v[66:67], off nt
	s_nop 0
	global_load_dwordx4 v[70:73], v[70:71], off nt
	s_nop 0
	global_load_dwordx4 v[74:77], v[74:75], off nt
	s_nop 0
	global_load_dwordx4 v[78:81], v[78:79], off nt
	s_nop 0
	global_load_dwordx4 v[82:85], v[82:83], off nt
	s_nop 0
	global_load_dwordx4 v[86:89], v[86:87], off nt
	s_nop 0
	global_load_dwordx4 v[90:93], v[90:91], off nt
	s_nop 0
	global_load_dwordx4 v[94:97], v[94:95], off nt
	s_nop 0
	global_load_dwordx4 v[98:101], v[98:99], off nt
	s_nop 0
	global_load_dwordx4 v[102:105], v[102:103], off nt
	s_nop 0
	global_load_dwordx4 v[106:109], v[106:107], off nt
	s_nop 0
	global_load_dwordx4 v[110:113], v[110:111], off nt
	s_nop 0
	global_load_dwordx4 v[114:117], v[114:115], off nt
	v_mul_u32_u24_e32 v2, s46, v23
	v_lshlrev_b32_e32 v2, 2, v2
	v_lshl_add_u64 v[118:119], v[122:123], 0, v[2:3]
	v_mul_u32_u24_e32 v2, s46, v24
	global_load_dwordx4 v[118:121], v[118:119], off nt
	v_lshlrev_b32_e32 v2, 2, v2
	v_lshl_add_u64 v[122:123], v[122:123], 0, v[2:3]
	global_load_dwordx4 v[122:125], v[122:123], off nt
	s_bitcmp1_b32 s98, 3
	s_cbranch_scc0 .Lit_nopend
; #define LAS __attribute__((address_space(3)))
; #define GAS __attribute__((address_space(1)))
; __device__ __forceinline__ unsigned cvt_pk_bf16(float lo, float hi) { unsigned r; asm volatile("v_cvt_pk_bf16_f32 %0, %1, %2" : "=v"(r) : "v"(lo), "v"(hi)); return r; }
; __device__ __forceinline__ void p0_transpose_item(const float* Wsrc  , int ldw, bf16_t* dst  , int ldt, LAS float* scr, int lane) {
;     ...
;     for (int j = 0; j < 8; ++j) { const int n = (lane >> 3) + 8 * j; const LAS float* s = scr + (8 * c) * 65 + n;
;         u32x4 o; o.x = cvt_pk_bf16(s[0 * 65], s[1 * 65]); o.y = cvt_pk_bf16(s[2 * 65], s[3 * 65]); o.z = cvt_pk_bf16(s[4 * 65], s[5 * 65]); o.w = cvt_pk_bf16(s[6 * 65], s[7 * 65]);
;         *(GAS u32x4*)(dst + (size_t)n * ldt + 8 * c) = o; }
	v_mov_b32_e32 v231, 0
	v_add_u32_e32 v224, 0x400, v26
	ds_read2_b32 v[128:129], v26 offset1:65
	ds_read2_b32 v[130:131], v26 offset0:130 offset1:195
	ds_read2_b32 v[132:133], v224 offset0:4 offset1:69
	ds_read2_b32 v[134:135], v224 offset0:134 offset1:199
	ds_read2_b32 v[136:137], v26 offset0:8 offset1:73
	ds_read2_b32 v[138:139], v26 offset0:138 offset1:203
	ds_read2_b32 v[140:141], v224 offset0:12 offset1:77
	ds_read2_b32 v[142:143], v224 offset0:142 offset1:207
	s_waitcnt lgkmcnt(0)
	v_cvt_pk_bf16_f32 v192, v128, v129
	v_cvt_pk_bf16_f32 v193, v130, v131
	v_cvt_pk_bf16_f32 v194, v132, v133
	v_cvt_pk_bf16_f32 v195, v134, v135
	v_cvt_pk_bf16_f32 v196, v136, v137
	v_cvt_pk_bf16_f32 v197, v138, v139
	v_cvt_pk_bf16_f32 v198, v140, v141
	v_cvt_pk_bf16_f32 v199, v142, v143
	v_mul_u32_u24_e32 v230, s99, v25
	v_lshl_add_u64 v[226:227], s[100:101], 0, v[8:9]
	v_lshlrev_b32_e32 v230, 1, v230
	v_lshl_add_u64 v[228:229], v[226:227], 0, v[230:231]
	global_store_dwordx4 v[228:229], v[192:195], off
	v_mul_u32_u24_e32 v230, s99, v27
	v_lshlrev_b32_e32 v230, 1, v230
	v_lshl_add_u64 v[228:229], v[226:227], 0, v[230:231]
	global_store_dwordx4 v[228:229], v[196:199], off
	ds_read2_b32 v[144:145], v26 offset0:16 offset1:81
	ds_read2_b32 v[146:147], v26 offset0:146 offset1:211
	ds_read2_b32 v[148:149], v224 offset0:20 offset1:85
	ds_read2_b32 v[150:151], v224 offset0:150 offset1:215
	ds_read2_b32 v[152:153], v26 offset0:24 offset1:89
	ds_read2_b32 v[154:155], v26 offset0:154 offset1:219
	ds_read2_b32 v[156:157], v224 offset0:28 offset1:93
	ds_read2_b32 v[158:159], v224 offset0:158 offset1:223
	s_waitcnt lgkmcnt(0)
	v_cvt_pk_bf16_f32 v200, v144, v145
	v_cvt_pk_bf16_f32 v201, v146, v147
	v_cvt_pk_bf16_f32 v202, v148, v149
	v_cvt_pk_bf16_f32 v203, v150, v151
	v_cvt_pk_bf16_f32 v204, v152, v153
	v_cvt_pk_bf16_f32 v205, v154, v155
	v_cvt_pk_bf16_f32 v206, v156, v157
	v_cvt_pk_bf16_f32 v207, v158, v159
	v_mul_u32_u24_e32 v230, s99, v28
	v_lshlrev_b32_e32 v230, 1, v230
	v_lshl_add_u64 v[228:229], v[226:227], 0, v[230:231]
	global_store_dwordx4 v[228:229], v[200:203], off
	v_mul_u32_u24_e32 v230, s99, v29
	v_lshlrev_b32_e32 v230, 1, v230
	v_lshl_add_u64 v[228:229], v[226:227], 0, v[230:231]
	global_store_dwordx4 v[228:229], v[204:207], off
	ds_read2_b32 v[160:161], v26 offset0:32 offset1:97
	ds_read2_b32 v[162:163], v26 offset0:162 offset1:227
	ds_read2_b32 v[164:165], v224 offset0:36 offset1:101
	ds_read2_b32 v[166:167], v224 offset0:166 offset1:231
	ds_read2_b32 v[168:169], v26 offset0:40 offset1:105
	ds_read2_b32 v[170:171], v26 offset0:170 offset1:235
	ds_read2_b32 v[172:173], v224 offset0:44 offset1:109
	ds_read2_b32 v[174:175], v224 offset0:174 offset1:239
	s_waitcnt lgkmcnt(0)
	v_cvt_pk_bf16_f32 v208, v160, v161
	v_cvt_pk_bf16_f32 v209, v162, v163
	v_cvt_pk_bf16_f32 v210, v164, v165
	v_cvt_pk_bf16_f32 v211, v166, v167
	v_cvt_pk_bf16_f32 v212, v168, v169
	v_cvt_pk_bf16_f32 v213, v170, v171
	v_cvt_pk_bf16_f32 v214, v172, v173
	v_cvt_pk_bf16_f32 v215, v174, v175
	v_mul_u32_u24_e32 v230, s99, v30
	v_lshlrev_b32_e32 v230, 1, v230
	v_lshl_add_u64 v[228:229], v[226:227], 0, v[230:231]
	global_store_dwordx4 v[228:229], v[208:211], off
	v_mul_u32_u24_e32 v230, s99, v31
	v_lshlrev_b32_e32 v230, 1, v230
	v_lshl_add_u64 v[228:229], v[226:227], 0, v[230:231]
	global_store_dwordx4 v[228:229], v[212:215], off
	ds_read2_b32 v[176:177], v26 offset0:48 offset1:113
	ds_read2_b32 v[178:179], v26 offset0:178 offset1:243
	ds_read2_b32 v[180:181], v224 offset0:52 offset1:117
	ds_read2_b32 v[182:183], v224 offset0:182 offset1:247
	ds_read2_b32 v[184:185], v26 offset0:56 offset1:121
	ds_read2_b32 v[186:187], v26 offset0:186 offset1:251
	ds_read2_b32 v[188:189], v224 offset0:60 offset1:125
	ds_read2_b32 v[190:191], v224 offset0:190 offset1:255
	s_waitcnt lgkmcnt(0)
	v_cvt_pk_bf16_f32 v216, v176, v177
	v_cvt_pk_bf16_f32 v217, v178, v179
	v_cvt_pk_bf16_f32 v218, v180, v181
	v_cvt_pk_bf16_f32 v219, v182, v183
	v_cvt_pk_bf16_f32 v220, v184, v185
	v_cvt_pk_bf16_f32 v221, v186, v187
	v_cvt_pk_bf16_f32 v222, v188, v189
	v_cvt_pk_bf16_f32 v223, v190, v191
	v_mul_u32_u24_e32 v230, s99, v32
	v_lshlrev_b32_e32 v230, 1, v230
	v_lshl_add_u64 v[228:229], v[226:227], 0, v[230:231]
	v_mul_u32_u24_e32 v230, s99, v33
	global_store_dwordx4 v[228:229], v[216:219], off
	v_lshlrev_b32_e32 v230, 1, v230
	v_lshl_add_u64 v[226:227], v[226:227], 0, v[230:231]
	global_store_dwordx4 v[226:227], v[220:223], off
	s_waitcnt vmcnt(8)
	s_branch .Lit_join

; #define LAS __attribute__((address_space(3)))
; #define GAS __attribute__((address_space(1)))
; #define LDS_WAIT() asm volatile("s_waitcnt lgkmcnt(0)" ::: "memory")
; __device__ __forceinline__ unsigned cvt_pk_bf16(float lo, float hi) { unsigned r; asm volatile("v_cvt_pk_bf16_f32 %0, %1, %2" : "=v"(r) : "v"(lo), "v"(hi)); return r; }
; __device__ __forceinline__ void p0_transpose_item(const float* Wsrc  , int ldw, bf16_t* dst  , int ldt, LAS float* scr, int lane) {
;     ...
;     for (int i = 0; i < 16; ++i) { LAS float* s = scr + (4 * i + r) * 65 + 4 * c4; s[0] = v[i].x; s[1] = v[i].y; s[2] = v[i].z; s[3] = v[i].w; }
;     LDS_WAIT(); asm volatile("" ::: "memory");
;     const int c = lane & 7;
; #pragma unroll
;     for (int j = 0; j < 8; ++j) { const int n = (lane >> 3) + 8 * j; const LAS float* s = scr + (8 * c) * 65 + n;
;         u32x4 o; o.x = cvt_pk_bf16(s[0 * 65], s[1 * 65]); o.y = cvt_pk_bf16(s[2 * 65], s[3 * 65]); o.z = cvt_pk_bf16(s[4 * 65], s[5 * 65]); o.w = cvt_pk_bf16(s[6 * 65], s[7 * 65]);
;         *(GAS u32x4*)(dst + (size_t)n * ldt + 8 * c) = o; }
;     LDS_WAIT(); asm volatile("" ::: "memory");
; }
.Lit_join:
	v_add_u32_e32 v2, 0x38e8, v34
	v_add_u32_e32 v126, 0x3cf0, v34
	v_add_u32_e32 v127, 0x3cf8, v34
	s_add_i32 s38, s54, 0x100
	s_add_i32 s55, s55, 0x4000
	s_addk_i32 s56, 0x400
	s_mov_b32 s54, s38
	ds_write2_b32 v34, v62, v63 offset1:1
	ds_write2_b32 v34, v64, v65 offset0:2 offset1:3
	ds_write2_b32 v35, v66, v67 offset1:1
	ds_write2_b32 v36, v68, v69 offset1:1
	ds_write2_b32 v37, v70, v71 offset1:1
	ds_write2_b32 v38, v72, v73 offset1:1
	ds_write2_b32 v39, v74, v75 offset1:1
	ds_write2_b32 v40, v76, v77 offset1:1
	ds_write2_b32 v41, v78, v79 offset1:1
	ds_write2_b32 v42, v80, v81 offset1:1
	ds_write2_b32 v43, v82, v83 offset1:1
	ds_write2_b32 v44, v84, v85 offset1:1
	ds_write2_b32 v45, v86, v87 offset1:1
	ds_write2_b32 v46, v88, v89 offset1:1
	ds_write2_b32 v47, v90, v91 offset1:1
	ds_write2_b32 v48, v92, v93 offset1:1
	ds_write2_b32 v49, v94, v95 offset1:1
	ds_write2_b32 v50, v96, v97 offset1:1
	ds_write2_b32 v51, v98, v99 offset1:1
	ds_write2_b32 v52, v100, v101 offset1:1
	ds_write2_b32 v53, v102, v103 offset1:1
	ds_write2_b32 v54, v104, v105 offset1:1
	ds_write2_b32 v55, v106, v107 offset1:1
	ds_write2_b32 v56, v108, v109 offset1:1
	ds_write2_b32 v57, v110, v111 offset1:1
	ds_write2_b32 v58, v112, v113 offset1:1
	ds_write2_b32 v59, v114, v115 offset1:1
	ds_write2_b32 v60, v116, v117 offset1:1
	ds_write2_b32 v61, v118, v119 offset1:1
	ds_write2_b32 v2, v120, v121 offset1:1
	ds_write2_b32 v126, v122, v123 offset1:1
	ds_write2_b32 v127, v124, v125 offset1:1
	s_waitcnt lgkmcnt(0)
	s_mov_b32 s99, s40
	s_mov_b64 s[100:101], s[42:43]
	s_bitset1_b32 s98, 3
	s_cmpk_lt_i32 s54, 0x40d0
	s_cbranch_scc1 .LBB0_316
	v_mov_b32_e32 v231, 0
	v_add_u32_e32 v224, 0x400, v26
	ds_read2_b32 v[128:129], v26 offset1:65
	ds_read2_b32 v[130:131], v26 offset0:130 offset1:195
	ds_read2_b32 v[132:133], v224 offset0:4 offset1:69
	ds_read2_b32 v[134:135], v224 offset0:134 offset1:199
	ds_read2_b32 v[136:137], v26 offset0:8 offset1:73
	ds_read2_b32 v[138:139], v26 offset0:138 offset1:203
	ds_read2_b32 v[140:141], v224 offset0:12 offset1:77
	ds_read2_b32 v[142:143], v224 offset0:142 offset1:207
	s_waitcnt lgkmcnt(0)
	v_cvt_pk_bf16_f32 v192, v128, v129
	v_cvt_pk_bf16_f32 v193, v130, v131
	v_cvt_pk_bf16_f32 v194, v132, v133
	v_cvt_pk_bf16_f32 v195, v134, v135
	v_cvt_pk_bf16_f32 v196, v136, v137
	v_cvt_pk_bf16_f32 v197, v138, v139
	v_cvt_pk_bf16_f32 v198, v140, v141
	v_cvt_pk_bf16_f32 v199, v142, v143
	v_mul_u32_u24_e32 v230, s99, v25
	v_lshl_add_u64 v[226:227], s[100:101], 0, v[8:9]
	v_lshlrev_b32_e32 v230, 1, v230
	v_lshl_add_u64 v[228:229], v[226:227], 0, v[230:231]
	global_store_dwordx4 v[228:229], v[192:195], off
	v_mul_u32_u24_e32 v230, s99, v27
	v_lshlrev_b32_e32 v230, 1, v230
	v_lshl_add_u64 v[228:229], v[226:227], 0, v[230:231]
	global_store_dwordx4 v[228:229], v[196:199], off
	ds_read2_b32 v[144:145], v26 offset0:16 offset1:81
	ds_read2_b32 v[146:147], v26 offset0:146 offset1:211
	ds_read2_b32 v[148:149], v224 offset0:20 offset1:85
	ds_read2_b32 v[150:151], v224 offset0:150 offset1:215
	ds_read2_b32 v[152:153], v26 offset0:24 offset1:89
	ds_read2_b32 v[154:155], v26 offset0:154 offset1:219
	ds_read2_b32 v[156:157], v224 offset0:28 offset1:93
	ds_read2_b32 v[158:159], v224 offset0:158 offset1:223
	s_waitcnt lgkmcnt(0)
	v_cvt_pk_bf16_f32 v200, v144, v145
	v_cvt_pk_bf16_f32 v201, v146, v147
	v_cvt_pk_bf16_f32 v202, v148, v149
	v_cvt_pk_bf16_f32 v203, v150, v151
	v_cvt_pk_bf16_f32 v204, v152, v153
	v_cvt_pk_bf16_f32 v205, v154, v155
	v_cvt_pk_bf16_f32 v206, v156, v157
	v_cvt_pk_bf16_f32 v207, v158, v159
	v_mul_u32_u24_e32 v230, s99, v28
	v_lshlrev_b32_e32 v230, 1, v230
	v_lshl_add_u64 v[228:229], v[226:227], 0, v[230:231]
	global_store_dwordx4 v[228:229], v[200:203], off
	v_mul_u32_u24_e32 v230, s99, v29
	v_lshlrev_b32_e32 v230, 1, v230
	v_lshl_add_u64 v[228:229], v[226:227], 0, v[230:231]
	global_store_dwordx4 v[228:229], v[204:207], off
	ds_read2_b32 v[160:161], v26 offset0:32 offset1:97
	ds_read2_b32 v[162:163], v26 offset0:162 offset1:227
	ds_read2_b32 v[164:165], v224 offset0:36 offset1:101
	ds_read2_b32 v[166:167], v224 offset0:166 offset1:231
	ds_read2_b32 v[168:169], v26 offset0:40 offset1:105
	ds_read2_b32 v[170:171], v26 offset0:170 offset1:235
	ds_read2_b32 v[172:173], v224 offset0:44 offset1:109
	ds_read2_b32 v[174:175], v224 offset0:174 offset1:239
	s_waitcnt lgkmcnt(0)
	v_cvt_pk_bf16_f32 v208, v160, v161
	v_cvt_pk_bf16_f32 v209, v162, v163
	v_cvt_pk_bf16_f32 v210, v164, v165
	v_cvt_pk_bf16_f32 v211, v166, v167
	v_cvt_pk_bf16_f32 v212, v168, v169
	v_cvt_pk_bf16_f32 v213, v170, v171
	v_cvt_pk_bf16_f32 v214, v172, v173
	v_cvt_pk_bf16_f32 v215, v174, v175
	v_mul_u32_u24_e32 v230, s99, v30
	v_lshlrev_b32_e32 v230, 1, v230
	v_lshl_add_u64 v[228:229], v[226:227], 0, v[230:231]
	global_store_dwordx4 v[228:229], v[208:211], off
	v_mul_u32_u24_e32 v230, s99, v31
	v_lshlrev_b32_e32 v230, 1, v230
	v_lshl_add_u64 v[228:229], v[226:227], 0, v[230:231]
	global_store_dwordx4 v[228:229], v[212:215], off
	ds_read2_b32 v[176:177], v26 offset0:48 offset1:113
	ds_read2_b32 v[178:179], v26 offset0:178 offset1:243
	ds_read2_b32 v[180:181], v224 offset0:52 offset1:117
	ds_read2_b32 v[182:183], v224 offset0:182 offset1:247
	ds_read2_b32 v[184:185], v26 offset0:56 offset1:121
	ds_read2_b32 v[186:187], v26 offset0:186 offset1:251
	ds_read2_b32 v[188:189], v224 offset0:60 offset1:125
	ds_read2_b32 v[190:191], v224 offset0:190 offset1:255
	s_waitcnt lgkmcnt(0)
	v_cvt_pk_bf16_f32 v216, v176, v177
	v_cvt_pk_bf16_f32 v217, v178, v179
	v_cvt_pk_bf16_f32 v218, v180, v181
	v_cvt_pk_bf16_f32 v219, v182, v183
	v_cvt_pk_bf16_f32 v220, v184, v185
	v_cvt_pk_bf16_f32 v221, v186, v187
	v_cvt_pk_bf16_f32 v222, v188, v189
	v_cvt_pk_bf16_f32 v223, v190, v191
	v_mul_u32_u24_e32 v230, s99, v32
	v_lshlrev_b32_e32 v230, 1, v230
	v_lshl_add_u64 v[228:229], v[226:227], 0, v[230:231]
	v_mul_u32_u24_e32 v230, s99, v33
	global_store_dwordx4 v[228:229], v[216:219], off
	v_lshlrev_b32_e32 v230, 1, v230
	v_lshl_add_u64 v[226:227], v[226:227], 0, v[230:231]
	global_store_dwordx4 v[226:227], v[220:223], off
	s_bitset0_b32 s98, 3
	s_branch .LBB0_340
; #define LAS __attribute__((address_space(3)))
; #define GAS __attribute__((address_space(1)))
; __device__ __forceinline__ unsigned cvt_pk_bf16(float lo, float hi) { unsigned r; asm volatile("v_cvt_pk_bf16_f32 %0, %1, %2" : "=v"(r) : "v"(lo), "v"(hi)); return r; }
; __device__ __forceinline__ void p0_transpose_item(const float* Wsrc  , int ldw, bf16_t* dst  , int ldt, LAS float* scr, int lane) {
;     ...
;     for (int j = 0; j < 8; ++j) { const int n = (lane >> 3) + 8 * j; const LAS float* s = scr + (8 * c) * 65 + n;
;         u32x4 o; o.x = cvt_pk_bf16(s[0 * 65], s[1 * 65]); o.y = cvt_pk_bf16(s[2 * 65], s[3 * 65]); o.z = cvt_pk_bf16(s[4 * 65], s[5 * 65]); o.w = cvt_pk_bf16(s[6 * 65], s[7 * 65]);
;         *(GAS u32x4*)(dst + (size_t)n * ldt + 8 * c) = o; }
; __device__ __forceinline__ void rms_row_to_bf16(const float* xrow, const float* g, bf16_t* orow, int lane) {
;     const GAS f32x4* xr = (const GAS f32x4*)xrow + lane;
;     f32x4 v[16], gv[16]; float s = 0.f;
;     const GAS f32x4* gr = (const GAS f32x4*)g + lane;
; #pragma unroll
;     for (int j = 0; j < 16; ++j) v[j] = __builtin_nontemporal_load(xr + 64 * j);
; #pragma unroll
;     for (int j = 0; j < 16; ++j) gv[j] = gr[64 * j];
.LBB0_316:
	s_cmpk_lt_u32 s54, 0x2e00
	s_cbranch_scc1 .Lkv_nopub
	s_bitcmp1_b32 s98, 4
	s_cbranch_scc1 .Lkv_nopub
	s_bitset1_b32 s98, 4
	s_bitcmp1_b32 s98, 3
	s_cbranch_scc0 .Lit_nofl
	v_mov_b32_e32 v231, 0
	v_add_u32_e32 v224, 0x400, v26
	ds_read2_b32 v[128:129], v26 offset1:65
	ds_read2_b32 v[130:131], v26 offset0:130 offset1:195
	ds_read2_b32 v[132:133], v224 offset0:4 offset1:69
	ds_read2_b32 v[134:135], v224 offset0:134 offset1:199
	ds_read2_b32 v[136:137], v26 offset0:8 offset1:73
	ds_read2_b32 v[138:139], v26 offset0:138 offset1:203
	ds_read2_b32 v[140:141], v224 offset0:12 offset1:77
	ds_read2_b32 v[142:143], v224 offset0:142 offset1:207
	s_waitcnt lgkmcnt(0)
	v_cvt_pk_bf16_f32 v192, v128, v129
	v_cvt_pk_bf16_f32 v193, v130, v131
	v_cvt_pk_bf16_f32 v194, v132, v133
	v_cvt_pk_bf16_f32 v195, v134, v135
	v_cvt_pk_bf16_f32 v196, v136, v137
	v_cvt_pk_bf16_f32 v197, v138, v139
	v_cvt_pk_bf16_f32 v198, v140, v141
	v_cvt_pk_bf16_f32 v199, v142, v143
	v_mul_u32_u24_e32 v230, s99, v25
	v_lshl_add_u64 v[226:227], s[100:101], 0, v[8:9]
	v_lshlrev_b32_e32 v230, 1, v230
	v_lshl_add_u64 v[228:229], v[226:227], 0, v[230:231]
	global_store_dwordx4 v[228:229], v[192:195], off
	v_mul_u32_u24_e32 v230, s99, v27
	v_lshlrev_b32_e32 v230, 1, v230
	v_lshl_add_u64 v[228:229], v[226:227], 0, v[230:231]
	global_store_dwordx4 v[228:229], v[196:199], off
	ds_read2_b32 v[144:145], v26 offset0:16 offset1:81
	ds_read2_b32 v[146:147], v26 offset0:146 offset1:211
	ds_read2_b32 v[148:149], v224 offset0:20 offset1:85
	ds_read2_b32 v[150:151], v224 offset0:150 offset1:215
	ds_read2_b32 v[152:153], v26 offset0:24 offset1:89
	ds_read2_b32 v[154:155], v26 offset0:154 offset1:219
	ds_read2_b32 v[156:157], v224 offset0:28 offset1:93
	ds_read2_b32 v[158:159], v224 offset0:158 offset1:223
	s_waitcnt lgkmcnt(0)
	v_cvt_pk_bf16_f32 v200, v144, v145
	v_cvt_pk_bf16_f32 v201, v146, v147
	v_cvt_pk_bf16_f32 v202, v148, v149
	v_cvt_pk_bf16_f32 v203, v150, v151
	v_cvt_pk_bf16_f32 v204, v152, v153
	v_cvt_pk_bf16_f32 v205, v154, v155
	v_cvt_pk_bf16_f32 v206, v156, v157
	v_cvt_pk_bf16_f32 v207, v158, v159
	v_mul_u32_u24_e32 v230, s99, v28
	v_lshlrev_b32_e32 v230, 1, v230
	v_lshl_add_u64 v[228:229], v[226:227], 0, v[230:231]
	global_store_dwordx4 v[228:229], v[200:203], off
	v_mul_u32_u24_e32 v230, s99, v29
	v_lshlrev_b32_e32 v230, 1, v230
	v_lshl_add_u64 v[228:229], v[226:227], 0, v[230:231]
	global_store_dwordx4 v[228:229], v[204:207], off
	ds_read2_b32 v[160:161], v26 offset0:32 offset1:97
	ds_read2_b32 v[162:163], v26 offset0:162 offset1:227
	ds_read2_b32 v[164:165], v224 offset0:36 offset1:101
	ds_read2_b32 v[166:167], v224 offset0:166 offset1:231
	ds_read2_b32 v[168:169], v26 offset0:40 offset1:105
	ds_read2_b32 v[170:171], v26 offset0:170 offset1:235
	ds_read2_b32 v[172:173], v224 offset0:44 offset1:109
	ds_read2_b32 v[174:175], v224 offset0:174 offset1:239
	s_waitcnt lgkmcnt(0)
	v_cvt_pk_bf16_f32 v208, v160, v161
	v_cvt_pk_bf16_f32 v209, v162, v163
	v_cvt_pk_bf16_f32 v210, v164, v165
	v_cvt_pk_bf16_f32 v211, v166, v167
	v_cvt_pk_bf16_f32 v212, v168, v169
	v_cvt_pk_bf16_f32 v213, v170, v171
	v_cvt_pk_bf16_f32 v214, v172, v173
	v_cvt_pk_bf16_f32 v215, v174, v175
	v_mul_u32_u24_e32 v230, s99, v30
	v_lshlrev_b32_e32 v230, 1, v230
	v_lshl_add_u64 v[228:229], v[226:227], 0, v[230:231]
	global_store_dwordx4 v[228:229], v[208:211], off
	v_mul_u32_u24_e32 v230, s99, v31
	v_lshlrev_b32_e32 v230, 1, v230
	v_lshl_add_u64 v[228:229], v[226:227], 0, v[230:231]
	global_store_dwordx4 v[228:229], v[212:215], off
	ds_read2_b32 v[176:177], v26 offset0:48 offset1:113
	ds_read2_b32 v[178:179], v26 offset0:178 offset1:243
	ds_read2_b32 v[180:181], v224 offset0:52 offset1:117
	ds_read2_b32 v[182:183], v224 offset0:182 offset1:247
	ds_read2_b32 v[184:185], v26 offset0:56 offset1:121
	ds_read2_b32 v[186:187], v26 offset0:186 offset1:251
	ds_read2_b32 v[188:189], v224 offset0:60 offset1:125
	ds_read2_b32 v[190:191], v224 offset0:190 offset1:255
	s_waitcnt lgkmcnt(0)
	v_cvt_pk_bf16_f32 v216, v176, v177
	v_cvt_pk_bf16_f32 v217, v178, v179
	v_cvt_pk_bf16_f32 v218, v180, v181
	v_cvt_pk_bf16_f32 v219, v182, v183
	v_cvt_pk_bf16_f32 v220, v184, v185
	v_cvt_pk_bf16_f32 v221, v186, v187
	v_cvt_pk_bf16_f32 v222, v188, v189
	v_cvt_pk_bf16_f32 v223, v190, v191
	v_mul_u32_u24_e32 v230, s99, v32
	v_lshlrev_b32_e32 v230, 1, v230
	v_lshl_add_u64 v[228:229], v[226:227], 0, v[230:231]
	v_mul_u32_u24_e32 v230, s99, v33
	global_store_dwordx4 v[228:229], v[216:219], off
	v_lshlrev_b32_e32 v230, 1, v230
	v_lshl_add_u64 v[226:227], v[226:227], 0, v[230:231]
	global_store_dwordx4 v[226:227], v[220:223], off
	s_bitset0_b32 s98, 3
.Lit_nofl:
	s_sub_u32 s99, s54, 0x2e00
	s_load_dwordx2 s[100:101], s[0:1], 0x40
	v_and_b32_e32 v192, 63, v0
	v_lshlrev_b32_e32 v194, 4, v192
	v_mov_b32_e32 v195, 0
	v_lshlrev_b32_e32 v202, 3, v192
	v_mov_b32_e32 v203, 0
	v_mov_b32_e32 v207, 0
	v_mov_b32_e32 v216, 0x358637bd
	v_mov_b32_e32 v217, 0x39800000
	v_mov_b32_e32 v218, 0x260
	v_mov_b32_e32 v219, 0xf800000
	s_waitcnt lgkmcnt(0)
	v_lshl_add_u64 v[196:197], s[100:101], 0, v[194:195]
	s_load_dwordx2 s[100:101], s[0:1], 0x8
	global_load_dwordx4 v[128:131], v[196:197], off offset:0
	global_load_dwordx4 v[132:135], v[196:197], off offset:1024
	global_load_dwordx4 v[136:139], v[196:197], off offset:2048
	global_load_dwordx4 v[140:143], v[196:197], off offset:3072
	v_add_co_u32_e32 v196, vcc, 0x1000, v196
	s_nop 1
	v_addc_co_u32_e32 v197, vcc, 0, v197, vcc
	global_load_dwordx4 v[144:147], v[196:197], off offset:0
	global_load_dwordx4 v[148:151], v[196:197], off offset:1024
	global_load_dwordx4 v[152:155], v[196:197], off offset:2048
	global_load_dwordx4 v[156:159], v[196:197], off offset:3072
	v_add_co_u32_e32 v196, vcc, 0x1000, v196
	s_nop 1
	v_addc_co_u32_e32 v197, vcc, 0, v197, vcc
	global_load_dwordx4 v[160:163], v[196:197], off offset:0
	global_load_dwordx4 v[164:167], v[196:197], off offset:1024
	global_load_dwordx4 v[168:171], v[196:197], off offset:2048
	global_load_dwordx4 v[172:175], v[196:197], off offset:3072
	v_add_co_u32_e32 v196, vcc, 0x1000, v196
	s_nop 1
	v_addc_co_u32_e32 v197, vcc, 0, v197, vcc
	global_load_dwordx4 v[176:179], v[196:197], off offset:0
	global_load_dwordx4 v[180:183], v[196:197], off offset:1024
	global_load_dwordx4 v[184:187], v[196:197], off offset:2048
	global_load_dwordx4 v[188:191], v[196:197], off offset:3072
	s_waitcnt lgkmcnt(0)
	v_lshl_add_u64 v[208:209], s[100:101], 0, v[194:195]
	s_add_u32 s100, s6, 0x1b200000
	s_addc_u32 s101, s7, 0
	v_lshl_add_u64 v[210:211], s[100:101], 0, v[202:203]
